# selected-branch PATH1/PATH2 tiles: K fragments read once and shared by both column blocks, both QK MFMA groups issued up front (cb0 scores in spare VGPRs)
# speedup vs baseline: 1.0044x; 1.0044x over previous
.LBB0_430:
	s_andn2_b64 vcc, exec, s[6:7]
	s_cbranch_vccnz .LBB0_438
	v_cmp_ne_u32_e32 vcc, 0, v139
	s_cbranch_vccz .Lsel_fast
	v_add_u32_e32 v54, s13, v196
	v_sub_u32_e32 v0, s14, v140
	v_add_u32_e32 v62, v54, v194
	v_add_u32_e32 v89, v54, v195
	v_lshl_add_u32 v0, v0, 2, v216
	s_cmp_lg_u64 s[44:45], 0
	s_movk_i32 s98, 0xfec
	s_cselect_b32 s98, 0xffc, s98
	v_add_u32_e32 v230, s98, v0
	v_add_u32_e32 v231, 0xfec, v0
	ds_read_b128 v[64:67], v62 offset:16384
	ds_read_b128 v[54:57], v89 offset:16384
	ds_read_b128 v[68:71], v62 offset:18432
	ds_read_b128 v[58:61], v89 offset:18432
	ds_read_b128 v[72:75], v62 offset:20480
	ds_read_b128 v[76:79], v89 offset:20480
	ds_read_b128 v[80:83], v62 offset:22528
	ds_read_b128 v[84:87], v89 offset:22528
	ds_read2_b32 v[90:91], v230 offset1:1
	ds_read2_b32 v[92:93], v230 offset0:2 offset1:3
	ds_read2_b32 v[94:95], v230 offset0:16 offset1:17
	ds_read2_b32 v[96:97], v230 offset0:18 offset1:19
	s_waitcnt lgkmcnt(4)
	ds_read2_b32 v[98:99], v230 offset0:32 offset1:33
	ds_read2_b32 v[100:101], v230 offset0:34 offset1:35
	ds_read2_b32 v[154:155], v230 offset0:48 offset1:49
	ds_read2_b32 v[156:157], v230 offset0:50 offset1:51
	s_cbranch_scc0 .Lp1v_m1
	v_mfma_f32_16x16x32_bf16 v[170:173], v[64:67], v[2:5], 0
	v_mfma_f32_16x16x32_bf16 v[174:177], v[68:71], v[2:5], 0
	v_mfma_f32_16x16x32_bf16 v[170:173], v[54:57], v[6:9], v[170:173]
	v_mfma_f32_16x16x32_bf16 v[178:181], v[72:75], v[2:5], 0
	v_mfma_f32_16x16x32_bf16 v[174:177], v[58:61], v[6:9], v[174:177]
	v_mfma_f32_16x16x32_bf16 v[182:185], v[80:83], v[2:5], 0
	v_mfma_f32_16x16x32_bf16 v[178:181], v[76:79], v[6:9], v[178:181]
	v_mfma_f32_16x16x32_bf16 v[182:185], v[84:87], v[6:9], v[182:185]
.Lp1v_m1:
	s_cmp_lg_u64 s[42:43], 0
	s_cbranch_scc0 .Lp1v_nom1
	v_mfma_f32_16x16x32_bf16 v[64:67], v[64:67], v[10:13], 0
	v_mfma_f32_16x16x32_bf16 v[68:71], v[68:71], v[10:13], 0
	v_mfma_f32_16x16x32_bf16 v[64:67], v[54:57], v[14:17], v[64:67]
	v_mfma_f32_16x16x32_bf16 v[72:75], v[72:75], v[10:13], 0
	v_mfma_f32_16x16x32_bf16 v[68:71], v[58:61], v[14:17], v[68:71]
	v_mfma_f32_16x16x32_bf16 v[80:83], v[80:83], v[10:13], 0
	v_mfma_f32_16x16x32_bf16 v[72:75], v[76:79], v[14:17], v[72:75]
	v_mfma_f32_16x16x32_bf16 v[80:83], v[84:87], v[14:17], v[80:83]
	s_branch .Lp1v_s0
.Lp1v_nom1:
	s_nop 7
	s_nop 7
.Lp1v_s0:
	s_cmp_lg_u64 s[44:45], 0
	s_cbranch_scc0 .Lp1v_z0
	s_waitcnt lgkmcnt(0)
	v_pk_fma_f32 v[170:171], v[170:171], s[36:37], v[90:91] op_sel_hi:[1,0,1]
	v_pk_fma_f32 v[172:173], v[172:173], s[36:37], v[92:93] op_sel_hi:[1,0,1]
	v_pk_fma_f32 v[174:175], v[174:175], s[36:37], v[94:95] op_sel_hi:[1,0,1]
	v_pk_fma_f32 v[176:177], v[176:177], s[36:37], v[96:97] op_sel_hi:[1,0,1]
	v_pk_fma_f32 v[178:179], v[178:179], s[36:37], v[98:99] op_sel_hi:[1,0,1]
	v_pk_fma_f32 v[180:181], v[180:181], s[36:37], v[100:101] op_sel_hi:[1,0,1]
	v_pk_fma_f32 v[182:183], v[182:183], s[36:37], v[154:155] op_sel_hi:[1,0,1]
	v_pk_fma_f32 v[184:185], v[184:185], s[36:37], v[156:157] op_sel_hi:[1,0,1]
	ds_read2_b32 v[90:91], v231 offset1:1
	ds_read2_b32 v[92:93], v231 offset0:2 offset1:3
	ds_read2_b32 v[94:95], v231 offset0:16 offset1:17
	ds_read2_b32 v[96:97], v231 offset0:18 offset1:19
	ds_read2_b32 v[98:99], v231 offset0:32 offset1:33
	ds_read2_b32 v[100:101], v231 offset0:34 offset1:35
	ds_read2_b32 v[154:155], v231 offset0:48 offset1:49
	ds_read2_b32 v[156:157], v231 offset0:50 offset1:51
	v_max3_f32 v186, v170, v171, v172
	v_max3_f32 v186, v186, v173, v174
	v_max3_f32 v186, v186, v175, v176
	v_max3_f32 v186, v186, v177, v178
	v_max3_f32 v186, v186, v179, v180
	v_max3_f32 v186, v186, v181, v182
	v_max3_f32 v186, v186, v183, v184
	v_max3_f32 v186, v186, v185, s29
	v_mov_b32_e32 v187, v186
	s_nop 1
	v_permlane16_swap_b32_e32 v186, v187
	v_max_f32_e32 v186, v186, v187
	v_mov_b32_e32 v187, v186
	s_nop 1
	v_permlane32_swap_b32_e32 v186, v187
	v_max_f32_e32 v186, v186, v187
	v_cndmask_b32_e64 v186, v148, v186, s[44:45]
	v_max_f32_e32 v187, v160, v186
	v_sub_f32_e32 v248, v160, v187
	v_exp_f32_e32 v236, v248
	v_cndmask_b32_e64 v246, v209, v187, s[44:45]
	v_mov_b32_e32 v160, v187
	v_pk_mul_f32 v[36:37], v[36:37], v[236:237] op_sel_hi:[1,0]
	v_pk_mul_f32 v[34:35], v[34:35], v[236:237] op_sel_hi:[1,0]
	v_pk_mul_f32 v[48:49], v[48:49], v[236:237] op_sel_hi:[1,0]
	v_pk_mul_f32 v[46:47], v[46:47], v[236:237] op_sel_hi:[1,0]
	v_pk_mul_f32 v[44:45], v[44:45], v[236:237] op_sel_hi:[1,0]
	v_pk_mul_f32 v[42:43], v[42:43], v[236:237] op_sel_hi:[1,0]
	v_pk_mul_f32 v[52:53], v[52:53], v[236:237] op_sel_hi:[1,0]
	v_pk_mul_f32 v[50:51], v[50:51], v[236:237] op_sel_hi:[1,0]
	v_pk_add_f32 v[170:171], v[170:171], v[246:247] op_sel_hi:[1,0] neg_lo:[0,1] neg_hi:[0,1]
	v_pk_add_f32 v[172:173], v[172:173], v[246:247] op_sel_hi:[1,0] neg_lo:[0,1] neg_hi:[0,1]
	v_pk_add_f32 v[174:175], v[174:175], v[246:247] op_sel_hi:[1,0] neg_lo:[0,1] neg_hi:[0,1]
	v_pk_add_f32 v[176:177], v[176:177], v[246:247] op_sel_hi:[1,0] neg_lo:[0,1] neg_hi:[0,1]
	v_pk_add_f32 v[178:179], v[178:179], v[246:247] op_sel_hi:[1,0] neg_lo:[0,1] neg_hi:[0,1]
	v_pk_add_f32 v[180:181], v[180:181], v[246:247] op_sel_hi:[1,0] neg_lo:[0,1] neg_hi:[0,1]
	v_pk_add_f32 v[182:183], v[182:183], v[246:247] op_sel_hi:[1,0] neg_lo:[0,1] neg_hi:[0,1]
	v_pk_add_f32 v[184:185], v[184:185], v[246:247] op_sel_hi:[1,0] neg_lo:[0,1] neg_hi:[0,1]
	v_exp_f32_e32 v170, v170
	v_exp_f32_e32 v171, v171
	v_exp_f32_e32 v172, v172
	v_exp_f32_e32 v173, v173
	v_exp_f32_e32 v174, v174
	v_exp_f32_e32 v175, v175
	v_exp_f32_e32 v176, v176
	v_exp_f32_e32 v177, v177
	v_exp_f32_e32 v178, v178
	v_exp_f32_e32 v179, v179
	v_exp_f32_e32 v180, v180
	v_exp_f32_e32 v181, v181
	v_exp_f32_e32 v182, v182
	v_exp_f32_e32 v183, v183
	v_exp_f32_e32 v184, v184
	v_exp_f32_e32 v185, v185
	s_nop 0
	v_pk_add_f32 v[238:239], v[170:171], v[172:173]
	v_pk_add_f32 v[240:241], v[174:175], v[176:177]
	v_pk_add_f32 v[242:243], v[178:179], v[180:181]
	v_pk_add_f32 v[244:245], v[182:183], v[184:185]
	v_pk_add_f32 v[238:239], v[238:239], v[240:241]
	v_pk_add_f32 v[242:243], v[242:243], v[244:245]
	s_nop 0
	v_pk_add_f32 v[238:239], v[238:239], v[242:243]
	s_nop 0
	v_add_f32_e32 v238, v238, v239
	v_fma_f32 v144, v144, v236, v238
	v_cvt_pk_bf16_f32 v58, v170, v171
	v_cvt_pk_bf16_f32 v59, v172, v173
	v_cvt_pk_bf16_f32 v60, v174, v175
	v_cvt_pk_bf16_f32 v61, v176, v177
	v_cvt_pk_bf16_f32 v54, v178, v179
	v_cvt_pk_bf16_f32 v55, v180, v181
	v_cvt_pk_bf16_f32 v56, v182, v183
	v_cvt_pk_bf16_f32 v57, v184, v185
	s_branch .Lp1v_s1
.Lp1v_z0:
	s_nop 7
	s_nop 7
	v_mov_b32_e32 v54, 0
	v_mov_b32_e32 v55, v54
	v_mov_b32_e32 v56, v54
	v_mov_b32_e32 v57, v54
	v_mov_b32_e32 v58, v54
	v_mov_b32_e32 v59, v54
	v_mov_b32_e32 v60, v54
	v_mov_b32_e32 v61, v54
.Lp1v_s1:
	s_cmp_lg_u64 s[42:43], 0
	s_cbranch_scc0 .LBB0_445
	s_waitcnt lgkmcnt(0)
	v_pk_fma_f32 v[64:65], v[64:65], s[36:37], v[90:91] op_sel_hi:[1,0,1]
	v_pk_fma_f32 v[66:67], v[66:67], s[36:37], v[92:93] op_sel_hi:[1,0,1]
	v_pk_fma_f32 v[68:69], v[68:69], s[36:37], v[94:95] op_sel_hi:[1,0,1]
	v_pk_fma_f32 v[70:71], v[70:71], s[36:37], v[96:97] op_sel_hi:[1,0,1]
	v_pk_fma_f32 v[72:73], v[72:73], s[36:37], v[98:99] op_sel_hi:[1,0,1]
	v_pk_fma_f32 v[74:75], v[74:75], s[36:37], v[100:101] op_sel_hi:[1,0,1]
	v_pk_fma_f32 v[80:81], v[80:81], s[36:37], v[154:155] op_sel_hi:[1,0,1]
	v_pk_fma_f32 v[82:83], v[82:83], s[36:37], v[156:157] op_sel_hi:[1,0,1]
	v_max3_f32 v76, v64, v65, v66
	v_max3_f32 v76, v76, v67, v68
	v_max3_f32 v76, v76, v69, v70
	v_max3_f32 v76, v76, v71, v72
	v_max3_f32 v76, v76, v73, v74
	v_max3_f32 v76, v76, v75, v80
	v_max3_f32 v76, v76, v81, v82
	v_max3_f32 v76, v76, v83, s29
	v_mov_b32_e32 v77, v76
	s_nop 1
	v_permlane16_swap_b32_e32 v76, v77
	v_max_f32_e32 v76, v76, v77
	v_mov_b32_e32 v77, v76
	s_nop 1
	v_permlane32_swap_b32_e32 v76, v77
	v_max_f32_e32 v76, v76, v77
	v_cndmask_b32_e64 v76, v148, v76, s[42:43]
	v_max_f32_e32 v77, v161, v76
	v_sub_f32_e32 v0, v161, v77
	v_exp_f32_e32 v0, v0
	v_cndmask_b32_e64 v78, v209, v77, s[42:43]
	v_mov_b32_e32 v161, v77
	v_pk_mul_f32 v[32:33], v[32:33], v[0:1] op_sel_hi:[1,0]
	v_pk_mul_f32 v[30:31], v[30:31], v[0:1] op_sel_hi:[1,0]
	v_pk_mul_f32 v[28:29], v[28:29], v[0:1] op_sel_hi:[1,0]
	v_pk_mul_f32 v[26:27], v[26:27], v[0:1] op_sel_hi:[1,0]
	v_pk_mul_f32 v[24:25], v[24:25], v[0:1] op_sel_hi:[1,0]
	v_pk_mul_f32 v[22:23], v[22:23], v[0:1] op_sel_hi:[1,0]
	v_pk_mul_f32 v[20:21], v[20:21], v[0:1] op_sel_hi:[1,0]
	v_pk_mul_f32 v[18:19], v[18:19], v[0:1] op_sel_hi:[1,0]
	v_pk_add_f32 v[64:65], v[64:65], v[78:79] op_sel_hi:[1,0] neg_lo:[0,1] neg_hi:[0,1]
	v_pk_add_f32 v[66:67], v[66:67], v[78:79] op_sel_hi:[1,0] neg_lo:[0,1] neg_hi:[0,1]
	v_pk_add_f32 v[68:69], v[68:69], v[78:79] op_sel_hi:[1,0] neg_lo:[0,1] neg_hi:[0,1]
	v_pk_add_f32 v[70:71], v[70:71], v[78:79] op_sel_hi:[1,0] neg_lo:[0,1] neg_hi:[0,1]
	v_pk_add_f32 v[72:73], v[72:73], v[78:79] op_sel_hi:[1,0] neg_lo:[0,1] neg_hi:[0,1]
	v_pk_add_f32 v[74:75], v[74:75], v[78:79] op_sel_hi:[1,0] neg_lo:[0,1] neg_hi:[0,1]
	v_pk_add_f32 v[80:81], v[80:81], v[78:79] op_sel_hi:[1,0] neg_lo:[0,1] neg_hi:[0,1]
	v_pk_add_f32 v[82:83], v[82:83], v[78:79] op_sel_hi:[1,0] neg_lo:[0,1] neg_hi:[0,1]
	v_exp_f32_e32 v64, v64
	v_exp_f32_e32 v65, v65
	v_exp_f32_e32 v66, v66
	v_exp_f32_e32 v67, v67
	v_exp_f32_e32 v68, v68
	v_exp_f32_e32 v69, v69
	v_exp_f32_e32 v70, v70
	v_exp_f32_e32 v71, v71
	v_exp_f32_e32 v72, v72
	v_exp_f32_e32 v73, v73
	v_exp_f32_e32 v74, v74
	v_exp_f32_e32 v75, v75
	v_exp_f32_e32 v80, v80
	v_exp_f32_e32 v81, v81
	v_exp_f32_e32 v82, v82
	v_exp_f32_e32 v83, v83
	s_nop 0
	v_pk_add_f32 v[84:85], v[64:65], v[66:67]
	v_pk_add_f32 v[86:87], v[68:69], v[70:71]
	v_pk_add_f32 v[76:77], v[72:73], v[74:75]
	v_pk_add_f32 v[78:79], v[80:81], v[82:83]
	v_pk_add_f32 v[84:85], v[84:85], v[86:87]
	v_pk_add_f32 v[76:77], v[76:77], v[78:79]
	s_nop 0
	v_pk_add_f32 v[84:85], v[84:85], v[76:77]
	s_nop 0
	v_add_f32_e32 v84, v84, v85
	v_fma_f32 v145, v145, v0, v84
	v_cvt_pk_bf16_f32 v67, v66, v67
	v_cvt_pk_bf16_f32 v66, v64, v65
	v_cvt_pk_bf16_f32 v68, v68, v69
	v_cvt_pk_bf16_f32 v69, v70, v71
	v_cvt_pk_bf16_f32 v62, v72, v73
	v_cvt_pk_bf16_f32 v63, v74, v75
	v_cvt_pk_bf16_f32 v64, v80, v81
	v_cvt_pk_bf16_f32 v65, v82, v83
	s_branch .LBB0_446

.LBB0_439:
	s_andn2_b64 vcc, exec, s[6:7]
	s_cbranch_vccnz .LBB0_448
	v_and_b32_e32 v0, 1, v164
	v_cmp_eq_u32_e64 s[42:43], 1, v0
	v_and_b32_e32 v0, 1, v162
	v_cmp_eq_u32_e64 s[44:45], 1, v0
	s_or_b64 s[6:7], s[44:45], s[42:43]
	v_cndmask_b32_e64 v54, 0, 1, s[6:7]
	v_cmp_ne_u32_e32 vcc, 0, v54
	s_cbranch_vccz .Lsel_fast
	v_add_u32_e32 v54, s13, v196
	v_add_u32_e32 v62, v54, v194
	v_add_u32_e32 v0, v54, v195
	s_cmp_lg_u64 s[44:45], 0
	ds_read_b128 v[64:67], v62 offset:16384
	ds_read_b128 v[54:57], v0 offset:16384
	ds_read_b128 v[68:71], v62 offset:18432
	ds_read_b128 v[58:61], v0 offset:18432
	ds_read_b128 v[72:75], v62 offset:20480
	ds_read_b128 v[76:79], v0 offset:20480
	ds_read_b128 v[80:83], v62 offset:22528
	ds_read_b128 v[84:87], v0 offset:22528
	ds_read_b32 v188, v193
	s_waitcnt lgkmcnt(0)
	s_cbranch_scc0 .Lp2v_m1
	v_mfma_f32_16x16x32_bf16 v[170:173], v[64:67], v[2:5], 0
	v_mfma_f32_16x16x32_bf16 v[174:177], v[68:71], v[2:5], 0
	v_mfma_f32_16x16x32_bf16 v[170:173], v[54:57], v[6:9], v[170:173]
	v_mfma_f32_16x16x32_bf16 v[178:181], v[72:75], v[2:5], 0
	v_mfma_f32_16x16x32_bf16 v[174:177], v[58:61], v[6:9], v[174:177]
	v_mfma_f32_16x16x32_bf16 v[182:185], v[80:83], v[2:5], 0
	v_mfma_f32_16x16x32_bf16 v[178:181], v[76:79], v[6:9], v[178:181]
	v_mfma_f32_16x16x32_bf16 v[182:185], v[84:87], v[6:9], v[182:185]

.Lp2v_s0:
	s_cmp_lg_u64 s[44:45], 0
	s_cbranch_scc0 .Lp2v_z0
	v_max3_f32 v186, v170, v171, v172
	v_max3_f32 v186, v186, v173, v174
	v_max3_f32 v186, v186, v175, v176
	v_max3_f32 v186, v186, v177, v178
	v_max3_f32 v186, v186, v179, v180
	v_max3_f32 v186, v186, v181, v182
	v_max3_f32 v186, v186, v183, v184
	v_max_f32_e32 v186, v186, v185
	v_mov_b32_e32 v187, v186
	s_nop 1
	v_permlane16_swap_b32_e32 v186, v187
	v_max_f32_e32 v186, v186, v187
	v_mov_b32_e32 v187, v186
	s_nop 1
	v_permlane32_swap_b32_e32 v186, v187
	v_max_f32_e32 v186, v186, v187
	v_fma_f32 v186, v186, s36, v188
	v_max_f32_e32 v186, s29, v186
	v_cndmask_b32_e64 v186, v148, v186, s[44:45]
	v_max_f32_e32 v187, v160, v186
	v_sub_f32_e32 v248, v160, v187
	v_exp_f32_e32 v236, v248
	v_cndmask_b32_e64 v186, v209, v187, s[44:45]
	v_mov_b32_e32 v160, v187
	v_sub_f32_e32 v246, v188, v186
	v_pk_mul_f32 v[36:37], v[36:37], v[236:237] op_sel_hi:[1,0]
	v_pk_mul_f32 v[34:35], v[34:35], v[236:237] op_sel_hi:[1,0]
	v_pk_mul_f32 v[48:49], v[48:49], v[236:237] op_sel_hi:[1,0]
	v_pk_mul_f32 v[46:47], v[46:47], v[236:237] op_sel_hi:[1,0]
	v_pk_mul_f32 v[44:45], v[44:45], v[236:237] op_sel_hi:[1,0]
	v_pk_mul_f32 v[42:43], v[42:43], v[236:237] op_sel_hi:[1,0]
	v_pk_mul_f32 v[52:53], v[52:53], v[236:237] op_sel_hi:[1,0]
	v_pk_mul_f32 v[50:51], v[50:51], v[236:237] op_sel_hi:[1,0]
	v_pk_fma_f32 v[170:171], v[170:171], s[36:37], v[246:247] op_sel_hi:[1,0,0]
	v_pk_fma_f32 v[172:173], v[172:173], s[36:37], v[246:247] op_sel_hi:[1,0,0]
	v_pk_fma_f32 v[174:175], v[174:175], s[36:37], v[246:247] op_sel_hi:[1,0,0]
	v_pk_fma_f32 v[176:177], v[176:177], s[36:37], v[246:247] op_sel_hi:[1,0,0]
	v_pk_fma_f32 v[178:179], v[178:179], s[36:37], v[246:247] op_sel_hi:[1,0,0]
	v_pk_fma_f32 v[180:181], v[180:181], s[36:37], v[246:247] op_sel_hi:[1,0,0]
	v_pk_fma_f32 v[182:183], v[182:183], s[36:37], v[246:247] op_sel_hi:[1,0,0]
	v_pk_fma_f32 v[184:185], v[184:185], s[36:37], v[246:247] op_sel_hi:[1,0,0]
	v_exp_f32_e32 v170, v170
	v_exp_f32_e32 v171, v171
	v_exp_f32_e32 v172, v172
	v_exp_f32_e32 v173, v173
	v_exp_f32_e32 v174, v174
	v_exp_f32_e32 v175, v175
	v_exp_f32_e32 v176, v176
	v_exp_f32_e32 v177, v177
	v_exp_f32_e32 v178, v178
	v_exp_f32_e32 v179, v179
	v_exp_f32_e32 v180, v180
	v_exp_f32_e32 v181, v181
	v_exp_f32_e32 v182, v182
	v_exp_f32_e32 v183, v183
	v_exp_f32_e32 v184, v184
	v_exp_f32_e32 v185, v185
	s_nop 0
	v_pk_add_f32 v[238:239], v[170:171], v[172:173]
	v_pk_add_f32 v[240:241], v[174:175], v[176:177]
	v_pk_add_f32 v[242:243], v[178:179], v[180:181]
	v_pk_add_f32 v[244:245], v[182:183], v[184:185]
	v_pk_add_f32 v[238:239], v[238:239], v[240:241]
	v_pk_add_f32 v[242:243], v[242:243], v[244:245]
	s_nop 0
	v_pk_add_f32 v[238:239], v[238:239], v[242:243]
	s_nop 0
	v_add_f32_e32 v238, v238, v239
	v_fma_f32 v144, v144, v236, v238
	v_cvt_pk_bf16_f32 v58, v170, v171
	v_cvt_pk_bf16_f32 v59, v172, v173
	v_cvt_pk_bf16_f32 v60, v174, v175
	v_cvt_pk_bf16_f32 v61, v176, v177
	v_cvt_pk_bf16_f32 v54, v178, v179
	v_cvt_pk_bf16_f32 v55, v180, v181
	v_cvt_pk_bf16_f32 v56, v182, v183
	v_cvt_pk_bf16_f32 v57, v184, v185
	s_branch .Lp2v_s1

.Lp2v_s1:
	s_cmp_lg_u64 s[42:43], 0
	s_cbranch_scc0 .LBB0_445
	v_max3_f32 v76, v64, v65, v66
	v_max3_f32 v76, v76, v67, v68
	v_max3_f32 v76, v76, v69, v70
	v_max3_f32 v76, v76, v71, v72
	v_max3_f32 v76, v76, v73, v74
	v_max3_f32 v76, v76, v75, v80
	v_max3_f32 v76, v76, v81, v82
	v_max_f32_e32 v76, v76, v83
	v_mov_b32_e32 v77, v76
	s_nop 1
	v_permlane16_swap_b32_e32 v76, v77
	v_max_f32_e32 v76, v76, v77
	v_mov_b32_e32 v77, v76
	s_nop 1
	v_permlane32_swap_b32_e32 v76, v77
	v_max_f32_e32 v76, v76, v77
	v_fma_f32 v76, v76, s36, v188
	v_max_f32_e32 v76, s29, v76
	v_cndmask_b32_e64 v76, v148, v76, s[42:43]
	v_max_f32_e32 v77, v161, v76
	v_sub_f32_e32 v0, v161, v77
	v_exp_f32_e32 v0, v0
	v_cndmask_b32_e64 v76, v209, v77, s[42:43]
	v_mov_b32_e32 v161, v77
	v_sub_f32_e32 v78, v188, v76
	v_pk_mul_f32 v[32:33], v[32:33], v[0:1] op_sel_hi:[1,0]
	v_pk_mul_f32 v[30:31], v[30:31], v[0:1] op_sel_hi:[1,0]
	v_pk_mul_f32 v[28:29], v[28:29], v[0:1] op_sel_hi:[1,0]
	v_pk_mul_f32 v[26:27], v[26:27], v[0:1] op_sel_hi:[1,0]
	v_pk_mul_f32 v[24:25], v[24:25], v[0:1] op_sel_hi:[1,0]
	v_pk_mul_f32 v[22:23], v[22:23], v[0:1] op_sel_hi:[1,0]
	v_pk_mul_f32 v[20:21], v[20:21], v[0:1] op_sel_hi:[1,0]
	v_pk_mul_f32 v[18:19], v[18:19], v[0:1] op_sel_hi:[1,0]
	v_pk_fma_f32 v[64:65], v[64:65], s[36:37], v[78:79] op_sel_hi:[1,0,0]
	v_pk_fma_f32 v[66:67], v[66:67], s[36:37], v[78:79] op_sel_hi:[1,0,0]
	v_pk_fma_f32 v[68:69], v[68:69], s[36:37], v[78:79] op_sel_hi:[1,0,0]
	v_pk_fma_f32 v[70:71], v[70:71], s[36:37], v[78:79] op_sel_hi:[1,0,0]
	v_pk_fma_f32 v[72:73], v[72:73], s[36:37], v[78:79] op_sel_hi:[1,0,0]
	v_pk_fma_f32 v[74:75], v[74:75], s[36:37], v[78:79] op_sel_hi:[1,0,0]
	v_pk_fma_f32 v[80:81], v[80:81], s[36:37], v[78:79] op_sel_hi:[1,0,0]
	v_pk_fma_f32 v[82:83], v[82:83], s[36:37], v[78:79] op_sel_hi:[1,0,0]
	v_exp_f32_e32 v64, v64
	v_exp_f32_e32 v65, v65
	v_exp_f32_e32 v66, v66
	v_exp_f32_e32 v67, v67
	v_exp_f32_e32 v68, v68
	v_exp_f32_e32 v69, v69
	v_exp_f32_e32 v70, v70
	v_exp_f32_e32 v71, v71
	v_exp_f32_e32 v72, v72
	v_exp_f32_e32 v73, v73
	v_exp_f32_e32 v74, v74
	v_exp_f32_e32 v75, v75
	v_exp_f32_e32 v80, v80
	v_exp_f32_e32 v81, v81
	v_exp_f32_e32 v82, v82
	v_exp_f32_e32 v83, v83
	s_nop 0
	v_pk_add_f32 v[84:85], v[64:65], v[66:67]
	v_pk_add_f32 v[86:87], v[68:69], v[70:71]
	v_pk_add_f32 v[76:77], v[72:73], v[74:75]
	v_pk_add_f32 v[78:79], v[80:81], v[82:83]
	v_pk_add_f32 v[84:85], v[84:85], v[86:87]
	v_pk_add_f32 v[76:77], v[76:77], v[78:79]
	s_nop 0
	v_pk_add_f32 v[84:85], v[84:85], v[76:77]
	s_nop 0
	v_add_f32_e32 v84, v84, v85
	v_fma_f32 v145, v145, v0, v84
	v_cvt_pk_bf16_f32 v67, v66, v67
	v_cvt_pk_bf16_f32 v66, v64, v65
	v_cvt_pk_bf16_f32 v68, v68, v69
	v_cvt_pk_bf16_f32 v69, v70, v71
	v_cvt_pk_bf16_f32 v62, v72, v73
	v_cvt_pk_bf16_f32 v63, v74, v75
	v_cvt_pk_bf16_f32 v64, v80, v81
	v_cvt_pk_bf16_f32 v65, v82, v83
	s_branch .LBB0_446
